# grid barrier: two-level arrival (one word per blockIdx&7 group, top word counts groups), pollers watch the top word generation; 7 of 8 in-loop sync sites
# speedup vs baseline: 1.1108x; 1.0370x over previous
; __global__ void __launch_bounds__(512) mega(Params P) {
;     ...
;     if (l > 0) { norm_phase(H, P.attn_norm + l * DM, HN); grid.sync(); }
.LBB0_225:
	s_or_b64 exec, exec, s[4:5]
	s_barrier
	s_mov_b64 s[2:3], exec
	v_readlane_b32 s0, v253, 57
	v_readlane_b32 s1, v253, 58
	s_and_b64 s[0:1], s[2:3], s[0:1]
	s_mov_b64 exec, s[0:1]
	s_cbranch_execz .LBB0_235
	buffer_wbl2 sc1
	s_waitcnt vmcnt(0)
	s_load_dwordx2 s[4:5], s[56:57], -0x8
	s_load_dword s0, s[56:57], 0x0
	v_readlane_b32 s1, v253, 55
	s_waitcnt lgkmcnt(0)
	s_and_b32 s1, s1, 7
	s_add_i32 s6, s0, 7
	s_sub_i32 s6, s6, s1
	s_lshr_b32 s6, s6, 3
	s_min_u32 s7, s0, 8
	s_lshl_b32 s1, s1, 2
	s_addk_i32 s1, 0x88
	v_mov_b32_e32 v2, s1
	global_load_dword v0, v1, s[4:5] sc1
	v_mov_b32_e32 v3, 1
	s_waitcnt vmcnt(0)
	v_and_b32_e32 v0, 0xffff0000, v0
	global_atomic_add v3, v2, v3, s[4:5] sc0
	s_waitcnt vmcnt(0)
	v_and_b32_e32 v3, 0xffff, v3
	s_nop 0
	v_readfirstlane_b32 s1, v3
	s_nop 3
	s_add_i32 s0, s6, -1
	s_cmp_lg_u32 s1, s0
	s_cbranch_scc1 .Lgb_poll_0
	s_sub_i32 s1, 0x10000, s6
	v_mov_b32_e32 v3, s1
	global_atomic_add v3, v2, v3, s[4:5] sc0
	s_waitcnt vmcnt(0)
	v_mov_b32_e32 v3, 1
	global_atomic_add v3, v1, v3, s[4:5] sc0
	s_waitcnt vmcnt(0)
	v_and_b32_e32 v3, 0xffff, v3
	s_nop 0
	v_readfirstlane_b32 s1, v3
	s_nop 3
	s_add_i32 s0, s7, -1
	s_cmp_lg_u32 s1, s0
	s_cbranch_scc1 .Lgb_poll_0
	s_sub_i32 s1, 0x10000, s7
	v_mov_b32_e32 v3, s1
	global_atomic_add v1, v3, s[4:5]
.Lgb_poll_0:
	global_load_dword v3, v1, s[4:5] sc1
	s_waitcnt vmcnt(0)
	v_and_b32_e32 v3, 0xffff0000, v3
	v_cmp_ne_u32_e32 vcc, v3, v0
	s_cbranch_vccnz .Lgb_done_0
	s_sleep 1
	s_branch .Lgb_poll_0

; __global__ void __launch_bounds__(512) mega(Params P) {
;     ...
;     grid.sync();
.LBB0_769:
	s_waitcnt vmcnt(0) lgkmcnt(0)
	s_barrier
	s_mov_b64 s[2:3], exec
	v_readlane_b32 s0, v253, 57
	v_readlane_b32 s1, v253, 58
	s_and_b64 s[0:1], s[2:3], s[0:1]
	s_mov_b64 exec, s[0:1]
	s_cbranch_execz .LBB0_779
	buffer_wbl2 sc1
	s_waitcnt vmcnt(0)
	s_load_dwordx2 s[4:5], s[56:57], -0x8
	s_load_dword s0, s[56:57], 0x0
	v_readlane_b32 s1, v253, 55
	s_waitcnt lgkmcnt(0)
	s_and_b32 s1, s1, 7
	s_add_i32 s6, s0, 7
	s_sub_i32 s6, s6, s1
	s_lshr_b32 s6, s6, 3
	s_min_u32 s7, s0, 8
	s_lshl_b32 s1, s1, 2
	s_addk_i32 s1, 0x88
	v_mov_b32_e32 v2, s1
	global_load_dword v0, v1, s[4:5] sc1
	v_mov_b32_e32 v3, 1
	s_waitcnt vmcnt(0)
	v_and_b32_e32 v0, 0xffff0000, v0
	global_atomic_add v3, v2, v3, s[4:5] sc0
	s_waitcnt vmcnt(0)
	v_and_b32_e32 v3, 0xffff, v3
	s_nop 0
	v_readfirstlane_b32 s1, v3
	s_nop 3
	s_add_i32 s0, s6, -1
	s_cmp_lg_u32 s1, s0
	s_cbranch_scc1 .Lgb_poll_1
	s_sub_i32 s1, 0x10000, s6
	v_mov_b32_e32 v3, s1
	global_atomic_add v3, v2, v3, s[4:5] sc0
	s_waitcnt vmcnt(0)
	v_mov_b32_e32 v3, 1
	global_atomic_add v3, v1, v3, s[4:5] sc0
	s_waitcnt vmcnt(0)
	v_and_b32_e32 v3, 0xffff, v3
	s_nop 0
	v_readfirstlane_b32 s1, v3
	s_nop 3
	s_add_i32 s0, s7, -1
	s_cmp_lg_u32 s1, s0
	s_cbranch_scc1 .Lgb_poll_1
	s_sub_i32 s1, 0x10000, s7
	v_mov_b32_e32 v3, s1
	global_atomic_add v1, v3, s[4:5]

; __global__ void __launch_bounds__(512) mega(Params P) {
;     ...
;     grid.sync();
.LBB0_1207:
	s_barrier
	s_mov_b64 s[2:3], exec
	v_readlane_b32 s0, v253, 57
	v_readlane_b32 s1, v253, 58
	s_and_b64 s[0:1], s[2:3], s[0:1]
	s_mov_b64 exec, s[0:1]
	s_cbranch_execz .LBB0_1217
	buffer_wbl2 sc1
	s_waitcnt vmcnt(0)
	s_load_dwordx2 s[4:5], s[56:57], -0x8
	s_load_dword s0, s[56:57], 0x0
	v_readlane_b32 s1, v253, 55
	s_waitcnt lgkmcnt(0)
	s_and_b32 s1, s1, 7
	s_add_i32 s6, s0, 7
	s_sub_i32 s6, s6, s1
	s_lshr_b32 s6, s6, 3
	s_min_u32 s7, s0, 8
	s_lshl_b32 s1, s1, 2
	s_addk_i32 s1, 0x88
	v_mov_b32_e32 v2, s1
	global_load_dword v0, v1, s[4:5] sc1
	v_mov_b32_e32 v3, 1
	s_waitcnt vmcnt(0)
	v_and_b32_e32 v0, 0xffff0000, v0
	global_atomic_add v3, v2, v3, s[4:5] sc0
	s_waitcnt vmcnt(0)
	v_and_b32_e32 v3, 0xffff, v3
	s_nop 0
	v_readfirstlane_b32 s1, v3
	s_nop 3
	s_add_i32 s0, s6, -1
	s_cmp_lg_u32 s1, s0
	s_cbranch_scc1 .Lgb_poll_2
	s_sub_i32 s1, 0x10000, s6
	v_mov_b32_e32 v3, s1
	global_atomic_add v3, v2, v3, s[4:5] sc0
	s_waitcnt vmcnt(0)
	v_mov_b32_e32 v3, 1
	global_atomic_add v3, v1, v3, s[4:5] sc0
	s_waitcnt vmcnt(0)
	v_and_b32_e32 v3, 0xffff, v3
	s_nop 0
	v_readfirstlane_b32 s1, v3
	s_nop 3
	s_add_i32 s0, s7, -1
	s_cmp_lg_u32 s1, s0
	s_cbranch_scc1 .Lgb_poll_2
	s_sub_i32 s1, 0x10000, s7
	v_mov_b32_e32 v3, s1
	global_atomic_add v1, v3, s[4:5]

; __global__ void __launch_bounds__(512) mega(Params P) {
;     ...
;     grid.sync();
.LBB0_1432:
	s_waitcnt lgkmcnt(0)
	s_barrier
	s_mov_b64 s[2:3], exec
	v_readlane_b32 s0, v253, 57
	v_readlane_b32 s1, v253, 58
	v_readlane_b32 s56, v254, 50
	s_and_b64 s[0:1], s[2:3], s[0:1]
	v_readlane_b32 s52, v254, 52
	v_readlane_b32 s57, v254, 51
	v_readlane_b32 s53, v254, 53
	s_mov_b64 exec, s[0:1]
	s_cbranch_execz .LBB0_1442
	buffer_wbl2 sc1
	s_waitcnt vmcnt(0)
	s_load_dwordx2 s[4:5], s[56:57], -0x8
	s_load_dword s0, s[56:57], 0x0
	v_readlane_b32 s1, v253, 55
	s_waitcnt lgkmcnt(0)
	s_and_b32 s1, s1, 7
	s_add_i32 s6, s0, 7
	s_sub_i32 s6, s6, s1
	s_lshr_b32 s6, s6, 3
	s_min_u32 s7, s0, 8
	s_lshl_b32 s1, s1, 2
	s_addk_i32 s1, 0x88
	v_mov_b32_e32 v2, s1
	global_load_dword v0, v1, s[4:5] sc1
	v_mov_b32_e32 v3, 1
	s_waitcnt vmcnt(0)
	v_and_b32_e32 v0, 0xffff0000, v0
	global_atomic_add v3, v2, v3, s[4:5] sc0
	s_waitcnt vmcnt(0)
	v_and_b32_e32 v3, 0xffff, v3
	s_nop 0
	v_readfirstlane_b32 s1, v3
	s_nop 3
	s_add_i32 s0, s6, -1
	s_cmp_lg_u32 s1, s0
	s_cbranch_scc1 .Lgb_poll_3
	s_sub_i32 s1, 0x10000, s6
	v_mov_b32_e32 v3, s1
	global_atomic_add v3, v2, v3, s[4:5] sc0
	s_waitcnt vmcnt(0)
	v_mov_b32_e32 v3, 1
	global_atomic_add v3, v1, v3, s[4:5] sc0
	s_waitcnt vmcnt(0)
	v_and_b32_e32 v3, 0xffff, v3
	s_nop 0
	v_readfirstlane_b32 s1, v3
	s_nop 3
	s_add_i32 s0, s7, -1
	s_cmp_lg_u32 s1, s0
	s_cbranch_scc1 .Lgb_poll_3
	s_sub_i32 s1, 0x10000, s7
	v_mov_b32_e32 v3, s1
	global_atomic_add v1, v3, s[4:5]

; __global__ void __launch_bounds__(512) mega(Params P) {
;     ...
;     grid.sync();
.LBB0_1489:
	s_waitcnt lgkmcnt(0)
	s_barrier
	s_mov_b64 s[4:5], exec
	v_readlane_b32 s0, v253, 57
	v_readlane_b32 s1, v253, 58
	s_and_b64 s[0:1], s[4:5], s[0:1]
	s_mov_b64 exec, s[0:1]
	s_cbranch_execz .LBB0_1499
	buffer_wbl2 sc1
	s_waitcnt vmcnt(0)
	s_load_dwordx2 s[6:7], s[56:57], -0x8
	s_load_dword s0, s[56:57], 0x0
	v_readlane_b32 s1, v253, 55
	s_waitcnt lgkmcnt(0)
	s_and_b32 s1, s1, 7
	s_add_i32 s8, s0, 7
	s_sub_i32 s8, s8, s1
	s_lshr_b32 s8, s8, 3
	s_min_u32 s9, s0, 8
	s_lshl_b32 s1, s1, 2
	s_addk_i32 s1, 0x88
	v_mov_b32_e32 v2, s1
	global_load_dword v0, v1, s[6:7] sc1
	v_mov_b32_e32 v3, 1
	s_waitcnt vmcnt(0)
	v_and_b32_e32 v0, 0xffff0000, v0
	global_atomic_add v3, v2, v3, s[6:7] sc0
	s_waitcnt vmcnt(0)
	v_and_b32_e32 v3, 0xffff, v3
	s_nop 0
	v_readfirstlane_b32 s1, v3
	s_nop 3
	s_add_i32 s0, s8, -1
	s_cmp_lg_u32 s1, s0
	s_cbranch_scc1 .Lgb_poll_4
	s_sub_i32 s1, 0x10000, s8
	v_mov_b32_e32 v3, s1
	global_atomic_add v3, v2, v3, s[6:7] sc0
	s_waitcnt vmcnt(0)
	v_mov_b32_e32 v3, 1
	global_atomic_add v3, v1, v3, s[6:7] sc0
	s_waitcnt vmcnt(0)
	v_and_b32_e32 v3, 0xffff, v3
	s_nop 0
	v_readfirstlane_b32 s1, v3
	s_nop 3
	s_add_i32 s0, s9, -1
	s_cmp_lg_u32 s1, s0
	s_cbranch_scc1 .Lgb_poll_4
	s_sub_i32 s1, 0x10000, s9
	v_mov_b32_e32 v3, s1
	global_atomic_add v1, v3, s[6:7]
.Lgb_poll_4:
	global_load_dword v3, v1, s[6:7] sc1
	s_waitcnt vmcnt(0)
	v_and_b32_e32 v3, 0xffff0000, v3
	v_cmp_ne_u32_e32 vcc, v3, v0
	s_cbranch_vccnz .Lgb_done_4
	s_sleep 1
	s_branch .Lgb_poll_4

; __global__ void __launch_bounds__(512) mega(Params P) {
;     ...
;     grid.sync();
.LBB0_1502:
	s_or_b64 exec, exec, s[6:7]
	s_barrier
	s_mov_b64 s[4:5], exec
	v_readlane_b32 s0, v253, 57
	v_readlane_b32 s1, v253, 58
	s_and_b64 s[0:1], s[4:5], s[0:1]
	s_mov_b64 exec, s[0:1]
	s_cbranch_execz .LBB0_1512
	buffer_wbl2 sc1
	s_waitcnt vmcnt(0)
	s_load_dwordx2 s[6:7], s[56:57], -0x8
	s_load_dword s0, s[56:57], 0x0
	v_readlane_b32 s1, v253, 55
	s_waitcnt lgkmcnt(0)
	s_and_b32 s1, s1, 7
	s_add_i32 s8, s0, 7
	s_sub_i32 s8, s8, s1
	s_lshr_b32 s8, s8, 3
	s_min_u32 s9, s0, 8
	s_lshl_b32 s1, s1, 2
	s_addk_i32 s1, 0x88
	v_mov_b32_e32 v2, s1
	global_load_dword v0, v1, s[6:7] sc1
	v_mov_b32_e32 v3, 1
	s_waitcnt vmcnt(0)
	v_and_b32_e32 v0, 0xffff0000, v0
	global_atomic_add v3, v2, v3, s[6:7] sc0
	s_waitcnt vmcnt(0)
	v_and_b32_e32 v3, 0xffff, v3
	s_nop 0
	v_readfirstlane_b32 s1, v3
	s_nop 3
	s_add_i32 s0, s8, -1
	s_cmp_lg_u32 s1, s0
	s_cbranch_scc1 .Lgb_poll_5
	s_sub_i32 s1, 0x10000, s8
	v_mov_b32_e32 v3, s1
	global_atomic_add v3, v2, v3, s[6:7] sc0
	s_waitcnt vmcnt(0)
	v_mov_b32_e32 v3, 1
	global_atomic_add v3, v1, v3, s[6:7] sc0
	s_waitcnt vmcnt(0)
	v_and_b32_e32 v3, 0xffff, v3
	s_nop 0
	v_readfirstlane_b32 s1, v3
	s_nop 3
	s_add_i32 s0, s9, -1
	s_cmp_lg_u32 s1, s0
	s_cbranch_scc1 .Lgb_poll_5
	s_sub_i32 s1, 0x10000, s9
	v_mov_b32_e32 v3, s1
	global_atomic_add v1, v3, s[6:7]

; __global__ void __launch_bounds__(512) mega(Params P) {
;     ...
;     grid.sync();
.LBB0_1534:
	s_waitcnt vmcnt(0) lgkmcnt(0)
	s_barrier
	s_mov_b64 s[4:5], exec
	v_readlane_b32 s0, v253, 57
	v_readlane_b32 s1, v253, 58
	s_and_b64 s[0:1], s[4:5], s[0:1]
	s_mov_b64 exec, s[0:1]
	s_cbranch_execz .LBB0_1544
	buffer_wbl2 sc1
	s_waitcnt vmcnt(0)
	s_load_dwordx2 s[6:7], s[56:57], -0x8
	s_load_dword s0, s[56:57], 0x0
	v_readlane_b32 s1, v253, 55
	s_waitcnt lgkmcnt(0)
	s_and_b32 s1, s1, 7
	s_add_i32 s8, s0, 7
	s_sub_i32 s8, s8, s1
	s_lshr_b32 s8, s8, 3
	s_min_u32 s9, s0, 8
	s_lshl_b32 s1, s1, 2
	s_addk_i32 s1, 0x88
	v_mov_b32_e32 v2, s1
	global_load_dword v0, v1, s[6:7] sc1
	v_mov_b32_e32 v3, 1
	s_waitcnt vmcnt(0)
	v_and_b32_e32 v0, 0xffff0000, v0
	global_atomic_add v3, v2, v3, s[6:7] sc0
	s_waitcnt vmcnt(0)
	v_and_b32_e32 v3, 0xffff, v3
	s_nop 0
	v_readfirstlane_b32 s1, v3
	s_nop 3
	s_add_i32 s0, s8, -1
	s_cmp_lg_u32 s1, s0
	s_cbranch_scc1 .Lgb_poll_6
	s_sub_i32 s1, 0x10000, s8
	v_mov_b32_e32 v3, s1
	global_atomic_add v3, v2, v3, s[6:7] sc0
	s_waitcnt vmcnt(0)
	v_mov_b32_e32 v3, 1
	global_atomic_add v3, v1, v3, s[6:7] sc0
	s_waitcnt vmcnt(0)
	v_and_b32_e32 v3, 0xffff, v3
	s_nop 0
	v_readfirstlane_b32 s1, v3
	s_nop 3
	s_add_i32 s0, s9, -1
	s_cmp_lg_u32 s1, s0
	s_cbranch_scc1 .Lgb_poll_6
	s_sub_i32 s1, 0x10000, s9
	v_mov_b32_e32 v3, s1
	global_atomic_add v1, v3, s[6:7]
